# baseline (speedup 1.0000x reference)
.LBB0_33:
	s_lshr_b32 s10, s27, 5
	v_cvt_f32_i32_e32 v10, s10
	s_sext_i32_i16 s8, s29
	v_cvt_f32_i32_e32 v11, s8
	s_ashr_i32 s8, s8, 30
	v_rcp_iflag_f32_e32 v15, v10
	s_or_b32 s28, s8, 1
	s_mov_b32 s3, 1
	s_mov_b32 s11, 0
	v_mul_f32_e32 v15, v11, v15
	v_trunc_f32_e32 v15, v15
	v_fma_f32 v11, -v15, v10, v11
	v_cvt_i32_f32_e32 v15, v15
	v_cmp_ge_f32_e64 s[8:9], |v11|, v10
	s_and_b64 s[8:9], s[8:9], exec
	s_cselect_b32 s8, s28, 0
	v_readfirstlane_b32 s9, v15
	s_add_i32 s8, s9, s8
	s_sext_i32_i16 s9, s8
	s_mul_i32 s8, s8, s10
	s_sub_i32 s8, s29, s8
	s_sext_i32_i16 s8, s8
	s_lshl_b32 s8, s8, 5
	s_lshl_b32 s10, s9, 6
	s_ashr_i32 s9, s8, 31
	s_lshl_b64 s[28:29], s[8:9], 2
	s_add_u32 s12, s12, s28
	s_addc_u32 s13, s13, s29
	s_lshl_b32 s29, s27, 2
	s_mul_i32 s28, s10, s29
	s_add_u32 s12, s12, s28
	s_addc_u32 s13, s13, 0
	s_lshl_b32 s30, s27, 3
	v_mul_lo_u32 v10, v2, s29
	v_mul_u32_u24_e32 v11, 0x84, v2
	v_add_u32_e32 v10, v10, v8
	v_add_u32_e32 v11, v11, v6
	global_load_dword v48, v10, s[12:13] nt
	s_add_u32 s12, s12, s30
	s_addc_u32 s13, s13, 0
	global_load_dword v49, v10, s[12:13] nt
	s_add_u32 s12, s12, s30
	s_addc_u32 s13, s13, 0
	global_load_dword v50, v10, s[12:13] nt
	s_add_u32 s12, s12, s30
	s_addc_u32 s13, s13, 0
	global_load_dword v51, v10, s[12:13] nt
	s_add_u32 s12, s12, s30
	s_addc_u32 s13, s13, 0
	global_load_dword v52, v10, s[12:13] nt
	s_add_u32 s12, s12, s30
	s_addc_u32 s13, s13, 0
	global_load_dword v53, v10, s[12:13] nt
	s_add_u32 s12, s12, s30
	s_addc_u32 s13, s13, 0
	global_load_dword v54, v10, s[12:13] nt
	s_add_u32 s12, s12, s30
	s_addc_u32 s13, s13, 0
	global_load_dword v55, v10, s[12:13] nt
	s_add_u32 s12, s12, s30
	s_addc_u32 s13, s13, 0
	global_load_dword v56, v10, s[12:13] nt
	s_add_u32 s12, s12, s30
	s_addc_u32 s13, s13, 0
	global_load_dword v57, v10, s[12:13] nt
	s_add_u32 s12, s12, s30
	s_addc_u32 s13, s13, 0
	global_load_dword v58, v10, s[12:13] nt
	s_add_u32 s12, s12, s30
	s_addc_u32 s13, s13, 0
	global_load_dword v59, v10, s[12:13] nt
	s_add_u32 s12, s12, s30
	s_addc_u32 s13, s13, 0
	global_load_dword v60, v10, s[12:13] nt
	s_add_u32 s12, s12, s30
	s_addc_u32 s13, s13, 0
	global_load_dword v61, v10, s[12:13] nt
	s_add_u32 s12, s12, s30
	s_addc_u32 s13, s13, 0
	global_load_dword v62, v10, s[12:13] nt
	s_add_u32 s12, s12, s30
	s_addc_u32 s13, s13, 0
	global_load_dword v63, v10, s[12:13] nt
	s_add_u32 s12, s12, s30
	s_addc_u32 s13, s13, 0
	global_load_dword v64, v10, s[12:13] nt
	s_add_u32 s12, s12, s30
	s_addc_u32 s13, s13, 0
	global_load_dword v65, v10, s[12:13] nt
	s_add_u32 s12, s12, s30
	s_addc_u32 s13, s13, 0
	global_load_dword v66, v10, s[12:13] nt
	s_add_u32 s12, s12, s30
	s_addc_u32 s13, s13, 0
	global_load_dword v67, v10, s[12:13] nt
	s_add_u32 s12, s12, s30
	s_addc_u32 s13, s13, 0
	global_load_dword v68, v10, s[12:13] nt
	s_add_u32 s12, s12, s30
	s_addc_u32 s13, s13, 0
	global_load_dword v69, v10, s[12:13] nt
	s_add_u32 s12, s12, s30
	s_addc_u32 s13, s13, 0
	global_load_dword v70, v10, s[12:13] nt
	s_add_u32 s12, s12, s30
	s_addc_u32 s13, s13, 0
	global_load_dword v71, v10, s[12:13] nt
	s_add_u32 s12, s12, s30
	s_addc_u32 s13, s13, 0
	global_load_dword v72, v10, s[12:13] nt
	s_add_u32 s12, s12, s30
	s_addc_u32 s13, s13, 0
	global_load_dword v73, v10, s[12:13] nt
	s_add_u32 s12, s12, s30
	s_addc_u32 s13, s13, 0
	global_load_dword v74, v10, s[12:13] nt
	s_add_u32 s12, s12, s30
	s_addc_u32 s13, s13, 0
	global_load_dword v75, v10, s[12:13] nt
	s_add_u32 s12, s12, s30
	s_addc_u32 s13, s13, 0
	global_load_dword v76, v10, s[12:13] nt
	s_add_u32 s12, s12, s30
	s_addc_u32 s13, s13, 0
	global_load_dword v77, v10, s[12:13] nt
	s_add_u32 s12, s12, s30
	s_addc_u32 s13, s13, 0
	global_load_dword v78, v10, s[12:13] nt
	s_add_u32 s12, s12, s30
	s_addc_u32 s13, s13, 0
	global_load_dword v79, v10, s[12:13] nt
	s_waitcnt vmcnt(31)
	ds_write_b32 v11, v48
	s_waitcnt vmcnt(30)
	ds_write_b32 v11, v49 offset:264
	s_waitcnt vmcnt(29)
	ds_write_b32 v11, v50 offset:528
	s_waitcnt vmcnt(28)
	ds_write_b32 v11, v51 offset:792
	s_waitcnt vmcnt(27)
	ds_write_b32 v11, v52 offset:1056
	s_waitcnt vmcnt(26)
	ds_write_b32 v11, v53 offset:1320
	s_waitcnt vmcnt(25)
	ds_write_b32 v11, v54 offset:1584
	s_waitcnt vmcnt(24)
	ds_write_b32 v11, v55 offset:1848
	s_waitcnt vmcnt(23)
	ds_write_b32 v11, v56 offset:2112
	s_waitcnt vmcnt(22)
	ds_write_b32 v11, v57 offset:2376
	s_waitcnt vmcnt(21)
	ds_write_b32 v11, v58 offset:2640
	s_waitcnt vmcnt(20)
	ds_write_b32 v11, v59 offset:2904
	s_waitcnt vmcnt(19)
	ds_write_b32 v11, v60 offset:3168
	s_waitcnt vmcnt(18)
	ds_write_b32 v11, v61 offset:3432
	s_waitcnt vmcnt(17)
	ds_write_b32 v11, v62 offset:3696
	s_waitcnt vmcnt(16)
	ds_write_b32 v11, v63 offset:3960
	s_waitcnt vmcnt(15)
	ds_write_b32 v11, v64 offset:4224
	s_waitcnt vmcnt(14)
	ds_write_b32 v11, v65 offset:4488
	s_waitcnt vmcnt(13)
	ds_write_b32 v11, v66 offset:4752
	s_waitcnt vmcnt(12)
	ds_write_b32 v11, v67 offset:5016
	s_waitcnt vmcnt(11)
	ds_write_b32 v11, v68 offset:5280
	s_waitcnt vmcnt(10)
	ds_write_b32 v11, v69 offset:5544
	s_waitcnt vmcnt(9)
	ds_write_b32 v11, v70 offset:5808
	s_waitcnt vmcnt(8)
	ds_write_b32 v11, v71 offset:6072
	s_waitcnt vmcnt(7)
	ds_write_b32 v11, v72 offset:6336
	s_waitcnt vmcnt(6)
	ds_write_b32 v11, v73 offset:6600
	s_waitcnt vmcnt(5)
	ds_write_b32 v11, v74 offset:6864
	s_waitcnt vmcnt(4)
	ds_write_b32 v11, v75 offset:7128
	s_waitcnt vmcnt(3)
	ds_write_b32 v11, v76 offset:7392
	s_waitcnt vmcnt(2)
	ds_write_b32 v11, v77 offset:7656
	s_waitcnt vmcnt(1)
	ds_write_b32 v11, v78 offset:7920
	s_waitcnt vmcnt(0)
	ds_write_b32 v11, v79 offset:8184
	s_lshl_b64 s[6:7], s[6:7], 1
	s_add_u32 s3, s4, s6
	s_addc_u32 s6, s5, s7
	s_ashr_i32 s11, s10, 31
	s_lshl_b64 s[4:5], s[10:11], 1
	s_add_u32 s4, s3, s4
	s_addc_u32 s5, s6, s5
	s_waitcnt lgkmcnt(0)
	ds_read2_b32 v[80:81], v7 offset0:0 offset1:33
	ds_read2_b32 v[82:83], v7 offset0:66 offset1:99
	ds_read2_b32 v[84:85], v7 offset0:132 offset1:165
	ds_read2_b32 v[86:87], v7 offset0:198 offset1:231
	ds_read2_b32 v[88:89], v7 offset0:8 offset1:41
	ds_read2_b32 v[90:91], v7 offset0:74 offset1:107
	ds_read2_b32 v[92:93], v7 offset0:140 offset1:173
	ds_read2_b32 v[94:95], v7 offset0:206 offset1:239
	ds_read2_b32 v[96:97], v7 offset0:16 offset1:49
	ds_read2_b32 v[98:99], v7 offset0:82 offset1:115
	ds_read2_b32 v[100:101], v7 offset0:148 offset1:181
	ds_read2_b32 v[102:103], v7 offset0:214 offset1:247
	ds_read2_b32 v[104:105], v7 offset0:24 offset1:57
	ds_read2_b32 v[106:107], v7 offset0:90 offset1:123
	ds_read2_b32 v[108:109], v7 offset0:156 offset1:189
	ds_read2_b32 v[110:111], v7 offset0:222 offset1:255
	v_lshl_add_u64 v[40:41], s[4:5], 0, v[4:5]
	v_or_b32_e32 v15, s8, v3
	v_mul_hi_i32_i24_e32 v43, s2, v15
	v_mul_i32_i24_e32 v42, s2, v15
	v_lshl_add_u64 v[32:33], v[42:43], 1, v[40:41]
	v_or_b32_e32 v15, s8, v12
	v_mul_hi_i32_i24_e32 v43, s2, v15
	v_mul_i32_i24_e32 v42, s2, v15
	v_lshl_add_u64 v[34:35], v[42:43], 1, v[40:41]
	v_or_b32_e32 v15, s8, v13
	v_mul_hi_i32_i24_e32 v43, s2, v15
	v_mul_i32_i24_e32 v42, s2, v15
	v_lshl_add_u64 v[36:37], v[42:43], 1, v[40:41]
	v_or_b32_e32 v15, s8, v14
	v_mul_hi_i32_i24_e32 v43, s2, v15
	v_mul_i32_i24_e32 v42, s2, v15
	v_lshl_add_u64 v[38:39], v[42:43], 1, v[40:41]
	s_waitcnt lgkmcnt(0)
	v_cvt_pk_bf16_f32 v16, v80, v81
	v_cvt_pk_bf16_f32 v17, v82, v83
	v_cvt_pk_bf16_f32 v18, v84, v85
	v_cvt_pk_bf16_f32 v19, v86, v87
	v_cvt_pk_bf16_f32 v20, v88, v89
	v_cvt_pk_bf16_f32 v21, v90, v91
	v_cvt_pk_bf16_f32 v22, v92, v93
	v_cvt_pk_bf16_f32 v23, v94, v95
	v_cvt_pk_bf16_f32 v24, v96, v97
	v_cvt_pk_bf16_f32 v25, v98, v99
	v_cvt_pk_bf16_f32 v26, v100, v101
	v_cvt_pk_bf16_f32 v27, v102, v103
	v_cvt_pk_bf16_f32 v28, v104, v105
	v_cvt_pk_bf16_f32 v29, v106, v107
	v_cvt_pk_bf16_f32 v30, v108, v109
	v_cvt_pk_bf16_f32 v31, v110, v111
	global_store_dwordx4 v[32:33], v[16:19], off nt
	global_store_dwordx4 v[34:35], v[20:23], off nt
	global_store_dwordx4 v[36:37], v[24:27], off nt
	global_store_dwordx4 v[38:39], v[28:31], off nt
	s_add_i32 s14, s14, s15
	s_cmp_lt_i32 s14, 0x1e800
	s_cbranch_scc1 .LBB0_11
	s_branch .LBB0_37
